# v108 plus per-segment priority flips in the DA attention loop (prio 1 across PV+QK MFMA regions, 0 across softmax)
# speedup vs baseline: 1.0027x; 1.0027x over previous
; __device__ __forceinline__ unsigned cvtpk(float lo, float hi) { f32x2_t v = {lo, hi}; bf16x2_t b = __builtin_convertvector(v, bf16x2_t); return __builtin_bit_cast(unsigned, b); }
; #define SBAR() __builtin_amdgcn_sched_barrier(0)
; template <bool ISSUE> ...
;     ...
;     const float off = mref - cb;
;     s0 = s0 - off; s1 = s1 - off;
; #pragma unroll
;     for (int r = 0; r < 16; ++r) { s0[r] = __builtin_amdgcn_exp2f(s0[r]); s1[r] = __builtin_amdgcn_exp2f(s1[r]); }
;     {
;         const f32x16 sm = s0 + s1;
;         lsum += ((sm[0] + sm[1]) + (sm[2] + sm[3])) + ((sm[4] + sm[5]) + (sm[6] + sm[7])) + (((sm[8] + sm[9]) + (sm[10] + sm[11])) + ((sm[12] + sm[13]) + (sm[14] + sm[15])));
;     }
;     bf16x8 p[4];
;     {
;         u32x4 w;
;         w.x = cvtpk(s0[0], s0[1]); w.y = cvtpk(s0[2], s0[3]); w.z = cvtpk(s0[4], s0[5]); w.w = cvtpk(s0[6], s0[7]); p[0] = __builtin_bit_cast(bf16x8, w);
;         w.x = cvtpk(s0[8], s0[9]); w.y = cvtpk(s0[10], s0[11]); w.z = cvtpk(s0[12], s0[13]); w.w = cvtpk(s0[14], s0[15]); p[1] = __builtin_bit_cast(bf16x8, w);
;         w.x = cvtpk(s1[0], s1[1]); w.y = cvtpk(s1[2], s1[3]); w.z = cvtpk(s1[4], s1[5]); w.w = cvtpk(s1[6], s1[7]); p[2] = __builtin_bit_cast(bf16x8, w);
;         w.x = cvtpk(s1[8], s1[9]); w.y = cvtpk(s1[10], s1[11]); w.z = cvtpk(s1[12], s1[13]); w.w = cvtpk(s1[14], s1[15]); p[3] = __builtin_bit_cast(bf16x8, w);
;     }
;     v_reads(vb, lds, vaddr, vb_ + 4096);
;     SBAR();
;     pv_rest<128>(o, p, va, vb, lds, vaddr, vb_);
; __device__ __forceinline__ void flash_da2(LAS unsigned char* lds, const bf16* __restrict__ Qw, const bf16* __restrict__ Kb, const bf16* __restrict__ VTb,
;                                           int NT, int qpos_w, f32x16 (&o)[4], float& mref, float& lsum) {
;     ...
;     for (int t = 0; t < NT; t += 2) {
;         da_tile<true>(lds, t, NT, qpos_w, r32, hi, qf, kaddr, vaddr, ksrc, vsrc, kdst, vdst, cls_cur, cb, o, mref, lsum);
;         da_tile<false>(lds, t + 1, NT, qpos_w, r32, hi, qf, kaddr, vaddr, ksrc, vsrc, kdst, vdst, cls_cur, cb, o, mref, lsum);
;         asm volatile("s_waitcnt vmcnt(0) lgkmcnt(0)\n\ts_barrier" ::: "memory");
;     }
.LBB0_427:
	v_sub_f32_e32 v14, v224, v225
	v_sub_f32_e32 v140, v109, v14
	v_sub_f32_e32 v105, v105, v14
	v_sub_f32_e32 v104, v104, v14
	v_sub_f32_e32 v15, v97, v14
	v_sub_f32_e32 v96, v96, v14
	v_sub_f32_e32 v109, v89, v14
	v_sub_f32_e32 v97, v88, v14
	v_sub_f32_e32 v81, v81, v14
	v_sub_f32_e32 v80, v80, v14
	v_sub_f32_e32 v133, v111, v14
	v_sub_f32_e32 v134, v110, v14
	v_sub_f32_e32 v132, v108, v14
	v_sub_f32_e32 v107, v107, v14
	v_sub_f32_e32 v106, v106, v14
	v_sub_f32_e32 v103, v103, v14
	v_sub_f32_e32 v102, v102, v14
	v_sub_f32_e32 v101, v101, v14
	v_sub_f32_e32 v100, v100, v14
	v_sub_f32_e32 v99, v99, v14
	v_sub_f32_e32 v98, v98, v14
	v_sub_f32_e32 v135, v95, v14
	v_sub_f32_e32 v141, v94, v14
	v_sub_f32_e32 v142, v93, v14
	v_sub_f32_e32 v143, v92, v14
	v_sub_f32_e32 v111, v91, v14
	v_sub_f32_e32 v110, v90, v14
	v_sub_f32_e32 v95, v87, v14
	v_sub_f32_e32 v87, v86, v14
	v_sub_f32_e32 v86, v85, v14
	v_sub_f32_e32 v85, v84, v14
	v_sub_f32_e32 v84, v83, v14
	v_sub_f32_e32 v83, v82, v14
	v_exp_f32_e32 v14, v96
	v_exp_f32_e32 v88, v80
	v_exp_f32_e32 v15, v15
	v_exp_f32_e32 v89, v81
	v_exp_f32_e32 v96, v104
	v_exp_f32_e32 v108, v97
	v_exp_f32_e32 v97, v105
	v_exp_f32_e32 v109, v109
	v_exp_f32_e32 v82, v98
	v_exp_f32_e32 v90, v83
	v_exp_f32_e32 v83, v99
	v_exp_f32_e32 v91, v84
	v_exp_f32_e32 v98, v106
	v_exp_f32_e32 v110, v110
	v_exp_f32_e32 v99, v107
	v_exp_f32_e32 v111, v111
	v_exp_f32_e32 v84, v100
	v_exp_f32_e32 v92, v85
	v_exp_f32_e32 v85, v101
	v_exp_f32_e32 v93, v86
	v_exp_f32_e32 v94, v87
	v_exp_f32_e32 v87, v103
	v_exp_f32_e32 v100, v132
	v_exp_f32_e32 v132, v143
	v_exp_f32_e32 v103, v133
	v_exp_f32_e32 v101, v140
	v_exp_f32_e32 v133, v142
	v_exp_f32_e32 v86, v102
	v_exp_f32_e32 v95, v95
	v_exp_f32_e32 v102, v134
	v_exp_f32_e32 v134, v141
	v_exp_f32_e32 v135, v135
	v_pk_add_f32 v[146:147], v[88:89], v[14:15]
	v_pk_add_f32 v[164:165], v[108:109], v[96:97]
	v_pk_add_f32 v[142:143], v[90:91], v[82:83]
	v_pk_add_f32 v[144:145], v[110:111], v[98:99]
	v_mov_b32_e32 v166, v146
	v_mov_b32_e32 v167, v164
	v_mov_b32_e32 v164, v147
	v_pk_add_f32 v[106:107], v[92:93], v[84:85]
	v_pk_add_f32 v[140:141], v[132:133], v[100:101]
	v_pk_add_f32 v[146:147], v[166:167], v[164:165]
	v_mov_b32_e32 v164, v142
	v_mov_b32_e32 v165, v144
	v_mov_b32_e32 v144, v143
	v_pk_add_f32 v[80:81], v[94:95], v[86:87]
	v_pk_add_f32 v[104:105], v[134:135], v[102:103]
	v_pk_add_f32 v[142:143], v[164:165], v[144:145]
	v_mov_b32_e32 v144, v106
	v_mov_b32_e32 v145, v140
	v_mov_b32_e32 v140, v107
	v_pk_add_f32 v[106:107], v[144:145], v[140:141]
	v_mov_b32_e32 v140, v80
	v_mov_b32_e32 v141, v104
	v_mov_b32_e32 v104, v81
	v_pk_add_f32 v[80:81], v[140:141], v[104:105]
	v_pk_add_f32 v[142:143], v[146:147], v[142:143]
	v_pk_add_f32 v[80:81], v[106:107], v[80:81]
	v_cvt_pk_bf16_f32 v88, v88, v89
	v_pk_add_f32 v[80:81], v[142:143], v[80:81]
	v_cvt_pk_bf16_f32 v89, v90, v91
	v_add_f32_e32 v80, v80, v81
	v_cvt_pk_bf16_f32 v81, v82, v83
	v_cvt_pk_bf16_f32 v82, v84, v85
	v_cvt_pk_bf16_f32 v83, v86, v87
	v_cvt_pk_bf16_f32 v84, v96, v97
	v_cvt_pk_bf16_f32 v85, v98, v99
	v_cvt_pk_bf16_f32 v86, v100, v101
	v_cvt_pk_bf16_f32 v87, v102, v103
	v_cvt_pk_bf16_f32 v90, v92, v93
	v_cvt_pk_bf16_f32 v91, v94, v95
	ds_read_b128 v[92:95], v136 offset:36864
	ds_read_b128 v[96:99], v137 offset:36864
	ds_read_b128 v[100:103], v138 offset:36864
	ds_read_b128 v[104:107], v139 offset:36864
	v_add_f32_e32 v0, v0, v80
	v_cvt_pk_bf16_f32 v80, v14, v15
	v_cvt_pk_bf16_f32 v108, v108, v109
	v_cvt_pk_bf16_f32 v109, v110, v111
	v_cvt_pk_bf16_f32 v110, v132, v133
	v_cvt_pk_bf16_f32 v111, v134, v135
	s_setprio 1
	s_waitcnt lgkmcnt(7)
	v_mfma_f32_32x32x16_bf16 v[64:79], v[6:9], v[80:83], v[64:79]
	s_waitcnt lgkmcnt(6)
	v_mfma_f32_32x32x16_bf16 v[64:79], v[2:5], v[84:87], v[64:79]
	s_waitcnt lgkmcnt(5)
	v_mfma_f32_32x32x16_bf16 v[64:79], v[10:13], v[88:91], v[64:79]
	s_waitcnt lgkmcnt(4)
	v_mfma_f32_32x32x16_bf16 v[64:79], v[128:131], v[108:111], v[64:79]
	ds_read_b128 v[2:5], v136 offset:40960
	ds_read_b128 v[6:9], v137 offset:40960
	ds_read_b128 v[10:13], v138 offset:40960
	ds_read_b128 v[128:131], v139 offset:40960
	s_waitcnt lgkmcnt(7)
	v_mfma_f32_32x32x16_bf16 v[48:63], v[92:95], v[80:83], v[48:63]
	s_waitcnt lgkmcnt(6)
	v_mfma_f32_32x32x16_bf16 v[48:63], v[96:99], v[84:87], v[48:63]
	s_waitcnt lgkmcnt(5)
	v_mfma_f32_32x32x16_bf16 v[48:63], v[100:103], v[88:91], v[48:63]
	s_waitcnt lgkmcnt(4)
	v_mfma_f32_32x32x16_bf16 v[48:63], v[104:107], v[108:111], v[48:63]
	ds_read_b128 v[92:95], v136 offset:45056
	ds_read_b128 v[96:99], v137 offset:45056
	ds_read_b128 v[100:103], v138 offset:45056
	ds_read_b128 v[104:107], v139 offset:45056
	s_waitcnt lgkmcnt(7)
	v_mfma_f32_32x32x16_bf16 v[32:47], v[2:5], v[80:83], v[32:47]
	s_waitcnt lgkmcnt(6)
	v_mfma_f32_32x32x16_bf16 v[32:47], v[6:9], v[84:87], v[32:47]
	s_waitcnt lgkmcnt(5)
	v_mfma_f32_32x32x16_bf16 v[32:47], v[10:13], v[88:91], v[32:47]
	s_waitcnt lgkmcnt(4)
	v_mfma_f32_32x32x16_bf16 v[32:47], v[128:131], v[108:111], v[32:47]
	s_waitcnt lgkmcnt(3)
	v_mfma_f32_32x32x16_bf16 v[16:31], v[92:95], v[80:83], v[16:31]
	s_waitcnt vmcnt(0) lgkmcnt(0)
	s_barrier
	s_add_i32 s8, s8, 2
	s_mov_b64 s[62:63], 0x8000
	s_addk_i32 s53, 0x80
	v_lshl_add_u64 v[160:161], v[160:161], 0, s[62:63]
	v_lshl_add_u64 v[162:163], v[162:163], 0, s[40:41]
	v_add_u32_e32 v223, 0x200, v223
	s_waitcnt lgkmcnt(2)
	v_mfma_f32_32x32x16_bf16 v[16:31], v[96:99], v[84:87], v[16:31]
	s_cmp_lt_u32 s66, s90
	s_waitcnt lgkmcnt(1)
	v_mfma_f32_32x32x16_bf16 v[16:31], v[100:103], v[88:91], v[16:31]
	s_waitcnt lgkmcnt(0)
	v_mfma_f32_32x32x16_bf16 v[16:31], v[104:107], v[108:111], v[16:31]
	s_cbranch_scc0 .LBB0_450

; #define LAS __attribute__((address_space(3)))
; #define SBAR() __builtin_amdgcn_sched_barrier(0)
; template <bool ISSUE> ...
;     ...
;     f32x16 s0, s1;
;     s0 = __builtin_amdgcn_mfma_f32_32x32x16_bf16(kf[0], qf[0], f32x16{}, 0, 0, 0);
;     s1 = __builtin_amdgcn_mfma_f32_32x32x16_bf16(kf[1], qf[0], f32x16{}, 0, 0, 0);
; #pragma unroll
;     for (int d0 = 1; d0 < 4; ++d0) {
;         s0 = __builtin_amdgcn_mfma_f32_32x32x16_bf16(kf[2 * d0], qf[d0], s0, 0, 0, 0);
;         s1 = __builtin_amdgcn_mfma_f32_32x32x16_bf16(kf[2 * d0 + 1], qf[d0], s1, 0, 0, 0);
;     }
;     bf16x8 va[4], vb[4];
;     v_reads(va, lds, vaddr, vb_);
;     SBAR();
;     if (cls == 0) {
;         int a0 = (kt + 16 * hi - (qpos_w + r32) + 129) * 4 + A_BT; asm volatile("" : "+v"(a0));
; #pragma unroll
;         for (int rg = 0; rg < 4; ++rg) {
; #pragma unroll
;             for (int r = 4 * rg; r < 4 * rg + 4; ++r) {
;                 const int aa = min(max(a0 + 4 * r, A_BT), A_BT + 258 * 4), ab = min(max(a0 + 4 * r + 128, A_BT), A_BT + 258 * 4);
;                 s0[r] += *(const LAS float*)(lds + aa);
;                 s1[r] += *(const LAS float*)(lds + ab);
;             }
;             SBAR();
;         }
;     }
.LBB0_434:
	s_waitcnt lgkmcnt(7)
	v_mfma_f32_32x32x16_bf16 v[96:111], v[80:83], v[112:115], 0
	s_add_i32 s67, s67, s66
	s_waitcnt lgkmcnt(6)
	v_mfma_f32_32x32x16_bf16 v[80:95], v[84:87], v[112:115], 0
	s_waitcnt lgkmcnt(5)
	v_mfma_f32_32x32x16_bf16 v[96:111], v[136:139], v[116:119], v[96:111]
	v_add_u32_e32 v136, s67, v212
	v_add_u32_e32 v138, s67, v214
	v_add_u32_e32 v137, s67, v213
	v_add_u32_e32 v139, s67, v215
	s_waitcnt lgkmcnt(4)
	v_mfma_f32_32x32x16_bf16 v[80:95], v[10:13], v[116:119], v[80:95]
	s_waitcnt lgkmcnt(3)
	v_mfma_f32_32x32x16_bf16 v[96:111], v[128:131], v[120:123], v[96:111]
	s_waitcnt lgkmcnt(2)
	v_mfma_f32_32x32x16_bf16 v[80:95], v[6:9], v[120:123], v[80:95]
	s_waitcnt lgkmcnt(1)
	v_mfma_f32_32x32x16_bf16 v[96:111], v[2:5], v[124:127], v[96:111]
	ds_read_b128 v[6:9], v136 offset:32768
	ds_read_b128 v[2:5], v137 offset:32768
	ds_read_b128 v[10:13], v138 offset:32768
	ds_read_b128 v[128:131], v139 offset:32768
	s_waitcnt lgkmcnt(4)
	v_mfma_f32_32x32x16_bf16 v[80:95], v[132:135], v[124:127], v[80:95]
	s_setprio 0
	s_cmp_lg_u32 s70, 0
	s_cbranch_scc1 .LBB0_436
	v_add_u32_e32 v174, 0xffffff00, v223
	s_nop 0
	v_add_u32_e32 v132, 4, v174
	v_med3_i32 v133, v132, s80, v219
	v_med3_i32 v132, v132, s84, v220
	v_add_u32_e32 v134, 0, v132
	v_add_u32_e32 v132, 8, v174
	v_med3_i32 v135, v132, s80, v219
	v_med3_i32 v132, v132, s84, v220
	v_add_u32_e32 v140, 0, v132
	v_add_u32_e32 v132, 12, v174
	v_med3_i32 v14, v174, s80, v219
	v_med3_i32 v15, v174, s84, v220
	v_med3_i32 v141, v132, s80, v219
	v_add_u32_e32 v14, 0, v14
	v_add_u32_e32 v15, 0, v15
	v_add_u32_e32 v133, 0, v133
	v_add_u32_e32 v135, 0, v135
	v_med3_i32 v132, v132, s84, v220
	v_add_u32_e32 v141, 0, v141
	v_add_u32_e32 v142, 0, v132
	ds_read_b32 v14, v14
	ds_read_b32 v132, v15 offset:128
	ds_read_b32 v15, v133
	ds_read_b32 v133, v134 offset:128
	ds_read_b32 v134, v135
	ds_read_b32 v140, v140 offset:128
	ds_read_b32 v135, v141
	ds_read_b32 v141, v142 offset:128
	v_add_u32_e32 v142, 16, v174
	v_med3_i32 v143, v142, s80, v219
	v_med3_i32 v142, v142, s84, v220
	v_add_u32_e32 v144, 0, v142
	v_add_u32_e32 v142, 20, v174
	v_med3_i32 v145, v142, s80, v219
	v_med3_i32 v142, v142, s84, v220
	v_add_u32_e32 v146, 0, v142
	v_add_u32_e32 v142, 24, v174
	v_med3_i32 v147, v142, s80, v219
	v_med3_i32 v142, v142, s84, v220
	v_add_u32_e32 v164, 0, v142
	v_add_u32_e32 v142, 28, v174
	v_med3_i32 v165, v142, s80, v219
	v_add_u32_e32 v143, 0, v143
	v_add_u32_e32 v145, 0, v145
	v_add_u32_e32 v147, 0, v147
	v_med3_i32 v142, v142, s84, v220
	v_add_u32_e32 v165, 0, v165
	v_add_u32_e32 v166, 0, v142
	ds_read_b32 v142, v143
	ds_read_b32 v144, v144 offset:128
	ds_read_b32 v143, v145
	ds_read_b32 v145, v146 offset:128
	ds_read_b32 v146, v147
	ds_read_b32 v164, v164 offset:128
	ds_read_b32 v147, v165
	ds_read_b32 v165, v166 offset:128
	v_add_u32_e32 v166, 32, v174
	v_med3_i32 v167, v166, s80, v219
	v_med3_i32 v166, v166, s84, v220
	v_add_u32_e32 v168, 0, v166
	v_add_u32_e32 v166, 36, v174
	v_med3_i32 v169, v166, s80, v219
	v_med3_i32 v166, v166, s84, v220
	v_add_u32_e32 v170, 0, v166
	v_add_u32_e32 v166, 40, v174
	v_med3_i32 v171, v166, s80, v219
	v_med3_i32 v166, v166, s84, v220
	v_add_u32_e32 v172, 0, v166
	v_add_u32_e32 v166, 44, v174
	v_med3_i32 v173, v166, s80, v219
	v_add_u32_e32 v167, 0, v167
	v_add_u32_e32 v169, 0, v169
	v_add_u32_e32 v171, 0, v171
	v_med3_i32 v166, v166, s84, v220
	v_add_u32_e32 v173, 0, v173
	v_add_u32_e32 v175, 0, v166
	ds_read_b32 v166, v167
	ds_read_b32 v168, v168 offset:128
	ds_read_b32 v167, v169
	ds_read_b32 v169, v170 offset:128
	ds_read_b32 v170, v171
	ds_read_b32 v172, v172 offset:128
	ds_read_b32 v171, v173
	ds_read_b32 v173, v175 offset:128
	v_add_u32_e32 v175, 48, v174
	v_add_u32_e32 v177, 52, v174
	v_add_u32_e32 v179, 56, v174
	v_add_u32_e32 v174, 60, v174
	v_med3_i32 v176, v175, s80, v219
	v_med3_i32 v181, v174, s80, v219
	v_med3_i32 v174, v174, s84, v220
	v_med3_i32 v175, v175, s84, v220
	v_add_u32_e32 v176, 0, v176
	v_med3_i32 v178, v177, s80, v219
	v_med3_i32 v177, v177, s84, v220
	v_med3_i32 v180, v179, s80, v219
	v_med3_i32 v179, v179, s84, v220
	s_waitcnt lgkmcnt(14)
	v_pk_add_f32 v[98:99], v[98:99], v[134:135]
	v_add_u32_e32 v135, 0, v174
	v_add_u32_e32 v175, 0, v175
	v_add_u32_e32 v178, 0, v178
	v_add_u32_e32 v177, 0, v177
	v_add_u32_e32 v180, 0, v180
	v_add_u32_e32 v179, 0, v179
	v_add_u32_e32 v181, 0, v181
	v_pk_add_f32 v[96:97], v[96:97], v[14:15]
	s_waitcnt lgkmcnt(9)
	v_pk_add_f32 v[102:103], v[102:103], v[146:147]
	v_pk_add_f32 v[100:101], v[100:101], v[142:143]
	ds_read_b32 v14, v176
	ds_read_b32 v134, v175 offset:128
	ds_read_b32 v142, v180
	ds_read_b32 v143, v181
	ds_read_b32 v15, v178
	ds_read_b32 v147, v135 offset:128
	ds_read_b32 v146, v179 offset:128
	ds_read_b32 v135, v177 offset:128
	s_waitcnt lgkmcnt(9)
	v_pk_add_f32 v[106:107], v[106:107], v[170:171]
	v_pk_add_f32 v[104:105], v[104:105], v[166:167]
	s_waitcnt lgkmcnt(4)
	v_pk_add_f32 v[110:111], v[110:111], v[142:143]
	s_waitcnt lgkmcnt(3)
	v_pk_add_f32 v[108:109], v[108:109], v[14:15]
	v_pk_add_f32 v[82:83], v[82:83], v[140:141]
	v_pk_add_f32 v[80:81], v[80:81], v[132:133]
	v_pk_add_f32 v[86:87], v[86:87], v[164:165]
	v_pk_add_f32 v[84:85], v[84:85], v[144:145]
	v_pk_add_f32 v[90:91], v[90:91], v[172:173]
	v_pk_add_f32 v[88:89], v[88:89], v[168:169]
	s_waitcnt lgkmcnt(1)
	v_pk_add_f32 v[94:95], v[94:95], v[146:147]
	s_waitcnt lgkmcnt(0)
	v_pk_add_f32 v[92:93], v[92:93], v[134:135]

; __device__ __forceinline__ unsigned cvtpk(float lo, float hi) { f32x2_t v = {lo, hi}; bf16x2_t b = __builtin_convertvector(v, bf16x2_t); return __builtin_bit_cast(unsigned, b); }
; #define SBAR() __builtin_amdgcn_sched_barrier(0)
; template <bool ISSUE> ...
;     ...
;     const float off = mref - cb;
;     s0 = s0 - off; s1 = s1 - off;
; #pragma unroll
;     for (int r = 0; r < 16; ++r) { s0[r] = __builtin_amdgcn_exp2f(s0[r]); s1[r] = __builtin_amdgcn_exp2f(s1[r]); }
;     {
;         const f32x16 sm = s0 + s1;
;         lsum += ((sm[0] + sm[1]) + (sm[2] + sm[3])) + ((sm[4] + sm[5]) + (sm[6] + sm[7])) + (((sm[8] + sm[9]) + (sm[10] + sm[11])) + ((sm[12] + sm[13]) + (sm[14] + sm[15])));
;     }
;     bf16x8 p[4];
;     {
;         u32x4 w;
;         w.x = cvtpk(s0[0], s0[1]); w.y = cvtpk(s0[2], s0[3]); w.z = cvtpk(s0[4], s0[5]); w.w = cvtpk(s0[6], s0[7]); p[0] = __builtin_bit_cast(bf16x8, w);
;         w.x = cvtpk(s0[8], s0[9]); w.y = cvtpk(s0[10], s0[11]); w.z = cvtpk(s0[12], s0[13]); w.w = cvtpk(s0[14], s0[15]); p[1] = __builtin_bit_cast(bf16x8, w);
;         w.x = cvtpk(s1[0], s1[1]); w.y = cvtpk(s1[2], s1[3]); w.z = cvtpk(s1[4], s1[5]); w.w = cvtpk(s1[6], s1[7]); p[2] = __builtin_bit_cast(bf16x8, w);
;         w.x = cvtpk(s1[8], s1[9]); w.y = cvtpk(s1[10], s1[11]); w.z = cvtpk(s1[12], s1[13]); w.w = cvtpk(s1[14], s1[15]); p[3] = __builtin_bit_cast(bf16x8, w);
;     }
;     v_reads(vb, lds, vaddr, vb_ + 4096);
;     SBAR();
;     pv_rest<128>(o, p, va, vb, lds, vaddr, vb_);
.LBB0_440:
	v_sub_f32_e32 v14, v224, v225
	v_sub_f32_e32 v107, v107, v14
	v_sub_f32_e32 v106, v106, v14
	v_sub_f32_e32 v105, v105, v14
	v_sub_f32_e32 v104, v104, v14
	v_sub_f32_e32 v103, v103, v14
	v_sub_f32_e32 v102, v102, v14
	v_sub_f32_e32 v101, v101, v14
	v_sub_f32_e32 v100, v100, v14
	v_sub_f32_e32 v99, v99, v14
	v_sub_f32_e32 v98, v98, v14
	v_sub_f32_e32 v96, v96, v14
	v_sub_f32_e32 v95, v95, v14
	v_sub_f32_e32 v94, v94, v14
	v_sub_f32_e32 v93, v93, v14
	v_sub_f32_e32 v92, v92, v14
	v_sub_f32_e32 v111, v111, v14
	v_sub_f32_e32 v110, v110, v14
	v_sub_f32_e32 v109, v109, v14
	v_sub_f32_e32 v108, v108, v14
	v_sub_f32_e32 v15, v97, v14
	v_sub_f32_e32 v91, v91, v14
	v_sub_f32_e32 v90, v90, v14
	v_sub_f32_e32 v89, v89, v14
	v_sub_f32_e32 v88, v88, v14
	v_sub_f32_e32 v87, v87, v14
	v_sub_f32_e32 v86, v86, v14
	v_sub_f32_e32 v85, v85, v14
	v_sub_f32_e32 v84, v84, v14
	v_sub_f32_e32 v83, v83, v14
	v_sub_f32_e32 v82, v82, v14
	v_sub_f32_e32 v81, v81, v14
	v_sub_f32_e32 v80, v80, v14
	v_exp_f32_e32 v14, v96
	v_exp_f32_e32 v166, v98
	v_exp_f32_e32 v167, v99
	v_exp_f32_e32 v170, v100
	v_exp_f32_e32 v171, v101
	v_exp_f32_e32 v174, v102
	v_exp_f32_e32 v175, v103
	v_exp_f32_e32 v178, v104
	v_exp_f32_e32 v179, v105
	v_exp_f32_e32 v182, v106
	v_exp_f32_e32 v183, v107
	v_exp_f32_e32 v188, v92
	v_exp_f32_e32 v189, v93
	v_exp_f32_e32 v192, v94
	v_exp_f32_e32 v193, v95
	ds_read_b128 v[92:95], v136 offset:36864
	ds_read_b128 v[96:99], v137 offset:36864
	ds_read_b128 v[100:103], v138 offset:36864
	ds_read_b128 v[104:107], v139 offset:36864
	v_exp_f32_e32 v164, v80
	v_exp_f32_e32 v15, v15
	v_exp_f32_e32 v165, v81
	v_exp_f32_e32 v168, v82
	v_exp_f32_e32 v169, v83
	v_exp_f32_e32 v172, v84
	v_exp_f32_e32 v173, v85
	v_exp_f32_e32 v176, v86
	v_exp_f32_e32 v177, v87
	v_exp_f32_e32 v180, v88
	v_exp_f32_e32 v181, v89
	v_exp_f32_e32 v184, v90
	v_exp_f32_e32 v185, v91
	v_exp_f32_e32 v186, v108
	v_exp_f32_e32 v187, v109
	v_exp_f32_e32 v190, v110
	v_exp_f32_e32 v191, v111
	v_cvt_pk_bf16_f32 v80, v14, v15
	v_cvt_pk_bf16_f32 v81, v166, v167
	v_cvt_pk_bf16_f32 v82, v170, v171
	v_cvt_pk_bf16_f32 v83, v174, v175
	v_cvt_pk_bf16_f32 v84, v178, v179
	v_cvt_pk_bf16_f32 v85, v182, v183
	v_cvt_pk_bf16_f32 v86, v186, v187
	v_cvt_pk_bf16_f32 v87, v190, v191
	v_cvt_pk_bf16_f32 v88, v164, v165
	v_cvt_pk_bf16_f32 v89, v168, v169
	v_cvt_pk_bf16_f32 v90, v172, v173
	v_cvt_pk_bf16_f32 v91, v176, v177
	v_cvt_pk_bf16_f32 v108, v180, v181
	v_cvt_pk_bf16_f32 v109, v184, v185
	v_cvt_pk_bf16_f32 v110, v188, v189
	v_cvt_pk_bf16_f32 v111, v192, v193
	s_setprio 1
	s_waitcnt lgkmcnt(7)
	v_mfma_f32_32x32x16_bf16 v[64:79], v[6:9], v[80:83], v[64:79]
	s_waitcnt lgkmcnt(6)
	v_mfma_f32_32x32x16_bf16 v[64:79], v[2:5], v[84:87], v[64:79]
	s_waitcnt lgkmcnt(5)
	v_mfma_f32_32x32x16_bf16 v[64:79], v[10:13], v[88:91], v[64:79]
	s_waitcnt lgkmcnt(4)
	v_mfma_f32_32x32x16_bf16 v[64:79], v[128:131], v[108:111], v[64:79]
	ds_read_b128 v[2:5], v136 offset:40960
	ds_read_b128 v[6:9], v137 offset:40960
	ds_read_b128 v[10:13], v138 offset:40960
	ds_read_b128 v[128:131], v139 offset:40960
	s_waitcnt lgkmcnt(7)
	v_mfma_f32_32x32x16_bf16 v[48:63], v[92:95], v[80:83], v[48:63]
	s_waitcnt lgkmcnt(6)
	v_mfma_f32_32x32x16_bf16 v[48:63], v[96:99], v[84:87], v[48:63]
	s_waitcnt lgkmcnt(5)
	v_mfma_f32_32x32x16_bf16 v[48:63], v[100:103], v[88:91], v[48:63]
	s_waitcnt lgkmcnt(4)
	v_mfma_f32_32x32x16_bf16 v[48:63], v[104:107], v[108:111], v[48:63]
	ds_read_b128 v[92:95], v136 offset:45056
	ds_read_b128 v[96:99], v137 offset:45056
	ds_read_b128 v[100:103], v138 offset:45056
	ds_read_b128 v[104:107], v139 offset:45056
	s_waitcnt lgkmcnt(7)
	v_mfma_f32_32x32x16_bf16 v[32:47], v[2:5], v[80:83], v[32:47]
	s_waitcnt lgkmcnt(6)
	v_mfma_f32_32x32x16_bf16 v[32:47], v[6:9], v[84:87], v[32:47]
	s_waitcnt lgkmcnt(5)
	v_mfma_f32_32x32x16_bf16 v[32:47], v[10:13], v[88:91], v[32:47]
	s_waitcnt lgkmcnt(4)
	v_mfma_f32_32x32x16_bf16 v[32:47], v[128:131], v[108:111], v[32:47]
	s_waitcnt lgkmcnt(3)
	v_mfma_f32_32x32x16_bf16 v[16:31], v[92:95], v[80:83], v[16:31]
	s_add_i32 s11, s8, -2
	s_and_b32 s11, s11, 3
	s_lshl_b32 s67, s11, 13
	s_add_i32 s70, s67, 0
	v_add_u32_e32 v6, s70, v206
	v_add_u32_e32 v10, s70, v207
	ds_read_b128 v[2:5], v6
	ds_read_b128 v[6:9], v6 offset:4096
	s_waitcnt lgkmcnt(4)
	v_mfma_f32_32x32x16_bf16 v[16:31], v[96:99], v[84:87], v[16:31]
	ds_read_b128 v[144:147], v10
	ds_read_b128 v[136:139], v10 offset:4096
	v_add_u32_e32 v10, s70, v208
	v_add_u32_e32 v80, s70, v209
	ds_read_b128 v[140:143], v10
	ds_read_b128 v[128:131], v10 offset:4096
	ds_read_b128 v[10:13], v80
	ds_read_b128 v[132:135], v80 offset:4096
	s_waitcnt lgkmcnt(9)
	v_mfma_f32_32x32x16_bf16 v[16:31], v[100:103], v[88:91], v[16:31]
	s_waitcnt lgkmcnt(8)
	v_mfma_f32_32x32x16_bf16 v[16:31], v[104:107], v[108:111], v[16:31]
	s_add_i32 s11, s53, 31
	s_cmpk_gt_i32 s53, 0x5a
	s_cselect_b32 s62, 2, 0
	s_cmpk_gt_i32 s11, 0xff66
	s_cselect_b32 s71, s62, 1
	s_cmp_eq_u32 s71, s10
	s_cbranch_scc1 .LBB0_446
	s_cmp_lt_i32 s71, 1
	v_mov_b32_e32 v225, 0
	s_mov_b32 s10, s71
	s_cbranch_scc1 .LBB0_446
	s_cmp_lg_u32 s71, 1
	s_cbranch_scc0 .LBB0_444
	v_mov_b32_e32 v80, s83
	ds_read_b32 v225, v80
	s_mov_b32 s10, 2
	s_cbranch_execz .LBB0_445
	s_branch .LBB0_446

; #define LAS __attribute__((address_space(3)))
; #define SBAR() __builtin_amdgcn_sched_barrier(0)
; template <bool ISSUE> ...
;     ...
;     f32x16 s0, s1;
;     s0 = __builtin_amdgcn_mfma_f32_32x32x16_bf16(kf[0], qf[0], f32x16{}, 0, 0, 0);
;     s1 = __builtin_amdgcn_mfma_f32_32x32x16_bf16(kf[1], qf[0], f32x16{}, 0, 0, 0);
; #pragma unroll
;     for (int d0 = 1; d0 < 4; ++d0) {
;         s0 = __builtin_amdgcn_mfma_f32_32x32x16_bf16(kf[2 * d0], qf[d0], s0, 0, 0, 0);
;         s1 = __builtin_amdgcn_mfma_f32_32x32x16_bf16(kf[2 * d0 + 1], qf[d0], s1, 0, 0, 0);
;     }
;     bf16x8 va[4], vb[4];
;     v_reads(va, lds, vaddr, vb_);
;     SBAR();
;     if (cls == 0) {
;         int a0 = (kt + 16 * hi - (qpos_w + r32) + 129) * 4 + A_BT; asm volatile("" : "+v"(a0));
; #pragma unroll
;         for (int rg = 0; rg < 4; ++rg) {
; #pragma unroll
;             for (int r = 4 * rg; r < 4 * rg + 4; ++r) {
;                 const int aa = min(max(a0 + 4 * r, A_BT), A_BT + 258 * 4), ab = min(max(a0 + 4 * r + 128, A_BT), A_BT + 258 * 4);
;                 s0[r] += *(const LAS float*)(lds + aa);
;                 s1[r] += *(const LAS float*)(lds + ab);
;             }
;             SBAR();
;         }
;     }
.LBB0_446:
	s_waitcnt lgkmcnt(7)
	v_mfma_f32_32x32x16_bf16 v[96:111], v[2:5], v[112:115], 0
	s_add_i32 s70, s70, s67
	s_waitcnt lgkmcnt(6)
	v_mfma_f32_32x32x16_bf16 v[80:95], v[6:9], v[112:115], 0
	s_waitcnt lgkmcnt(5)
	v_mfma_f32_32x32x16_bf16 v[96:111], v[144:147], v[116:119], v[96:111]
	s_waitcnt lgkmcnt(4)
	v_mfma_f32_32x32x16_bf16 v[80:95], v[136:139], v[116:119], v[80:95]
	v_add_u32_e32 v136, s70, v212
	v_add_u32_e32 v138, s70, v214
	v_add_u32_e32 v137, s70, v213
	ds_read_b128 v[6:9], v136 offset:32768
	ds_read_b128 v[2:5], v137 offset:32768
	v_add_u32_e32 v139, s70, v215
	s_waitcnt lgkmcnt(5)
	v_mfma_f32_32x32x16_bf16 v[96:111], v[140:143], v[120:123], v[96:111]
	s_waitcnt lgkmcnt(4)
	v_mfma_f32_32x32x16_bf16 v[80:95], v[128:131], v[120:123], v[80:95]
	s_waitcnt lgkmcnt(3)
	v_mfma_f32_32x32x16_bf16 v[96:111], v[10:13], v[124:127], v[96:111]
	ds_read_b128 v[10:13], v138 offset:32768
	ds_read_b128 v[128:131], v139 offset:32768
	s_waitcnt lgkmcnt(4)
	v_mfma_f32_32x32x16_bf16 v[80:95], v[132:135], v[124:127], v[80:95]
	s_setprio 0
	s_cmp_lg_u32 s71, 0
	s_cbranch_scc1 .LBB0_448
	v_mov_b32_e32 v238, v223
	s_nop 0
	v_add_u32_e32 v134, 4, v238
	v_med3_i32 v135, v134, s80, v219
	v_med3_i32 v134, v134, s84, v220
	v_add_u32_e32 v140, 0, v134
	v_add_u32_e32 v134, 8, v238
	v_med3_i32 v141, v134, s80, v219
	v_med3_i32 v134, v134, s84, v220
	v_add_u32_e32 v142, 0, v134
	v_add_u32_e32 v134, 12, v238
	v_med3_i32 v132, v238, s80, v219
	v_med3_i32 v133, v238, s84, v220
	v_med3_i32 v143, v134, s80, v219
	v_add_u32_e32 v132, 0, v132
	v_add_u32_e32 v133, 0, v133
	v_add_u32_e32 v135, 0, v135
	v_add_u32_e32 v141, 0, v141
	v_med3_i32 v134, v134, s84, v220
	v_add_u32_e32 v143, 0, v143
	v_add_u32_e32 v144, 0, v134
	ds_read_b32 v132, v132
	ds_read_b32 v134, v133 offset:128
	ds_read_b32 v133, v135
	ds_read_b32 v135, v140 offset:128
	ds_read_b32 v140, v141
	ds_read_b32 v142, v142 offset:128
	ds_read_b32 v141, v143
	ds_read_b32 v143, v144 offset:128
	v_add_u32_e32 v144, 16, v238
	v_med3_i32 v145, v144, s80, v219
	v_med3_i32 v144, v144, s84, v220
	v_add_u32_e32 v146, 0, v144
	v_add_u32_e32 v144, 20, v238
	v_med3_i32 v147, v144, s80, v219
	v_med3_i32 v144, v144, s84, v220
	v_add_u32_e32 v226, 0, v144
	v_add_u32_e32 v144, 24, v238
	v_med3_i32 v227, v144, s80, v219
	v_med3_i32 v144, v144, s84, v220
	v_add_u32_e32 v228, 0, v144
	v_add_u32_e32 v144, 28, v238
	v_med3_i32 v229, v144, s80, v219
	v_add_u32_e32 v145, 0, v145
	v_add_u32_e32 v147, 0, v147
	v_add_u32_e32 v227, 0, v227
	v_med3_i32 v144, v144, s84, v220
	v_add_u32_e32 v229, 0, v229
	v_add_u32_e32 v230, 0, v144
	ds_read_b32 v144, v145
	ds_read_b32 v146, v146 offset:128
	ds_read_b32 v145, v147
	ds_read_b32 v147, v226 offset:128
	ds_read_b32 v226, v227
	ds_read_b32 v228, v228 offset:128
	ds_read_b32 v227, v229
	ds_read_b32 v229, v230 offset:128
	v_add_u32_e32 v230, 32, v238
	v_med3_i32 v231, v230, s80, v219
	v_med3_i32 v230, v230, s84, v220
	v_add_u32_e32 v232, 0, v230
	v_add_u32_e32 v230, 36, v238
	v_med3_i32 v233, v230, s80, v219
	v_med3_i32 v230, v230, s84, v220
	v_add_u32_e32 v234, 0, v230
	v_add_u32_e32 v230, 40, v238
	v_med3_i32 v235, v230, s80, v219
	v_med3_i32 v230, v230, s84, v220
	v_add_u32_e32 v236, 0, v230
	v_add_u32_e32 v230, 44, v238
	v_med3_i32 v237, v230, s80, v219
	v_add_u32_e32 v231, 0, v231
	v_add_u32_e32 v233, 0, v233
	v_add_u32_e32 v235, 0, v235
	v_med3_i32 v230, v230, s84, v220
	v_add_u32_e32 v237, 0, v237
	v_add_u32_e32 v239, 0, v230
	ds_read_b32 v230, v231
	ds_read_b32 v232, v232 offset:128
	ds_read_b32 v231, v233
	ds_read_b32 v233, v234 offset:128
	ds_read_b32 v234, v235
	ds_read_b32 v236, v236 offset:128
	ds_read_b32 v235, v237
	ds_read_b32 v237, v239 offset:128
	v_add_u32_e32 v239, 48, v238
	v_add_u32_e32 v241, 52, v238
	v_add_u32_e32 v243, 56, v238
	v_add_u32_e32 v238, 60, v238
	v_med3_i32 v240, v239, s80, v219
	v_med3_i32 v245, v238, s80, v219
	v_med3_i32 v238, v238, s84, v220
	v_med3_i32 v239, v239, s84, v220
	v_add_u32_e32 v240, 0, v240
	v_med3_i32 v242, v241, s80, v219
	v_med3_i32 v241, v241, s84, v220
	v_med3_i32 v244, v243, s80, v219
	v_med3_i32 v243, v243, s84, v220
	s_waitcnt lgkmcnt(14)
	v_pk_add_f32 v[98:99], v[98:99], v[140:141]
	v_add_u32_e32 v141, 0, v238
	v_add_u32_e32 v239, 0, v239
	v_add_u32_e32 v242, 0, v242
	v_add_u32_e32 v241, 0, v241
	v_add_u32_e32 v244, 0, v244
	v_add_u32_e32 v243, 0, v243
	v_add_u32_e32 v245, 0, v245
	v_pk_add_f32 v[96:97], v[96:97], v[132:133]
	s_waitcnt lgkmcnt(9)
	v_pk_add_f32 v[102:103], v[102:103], v[226:227]
	v_pk_add_f32 v[100:101], v[100:101], v[144:145]
	ds_read_b32 v132, v240
	ds_read_b32 v140, v239 offset:128
	ds_read_b32 v144, v244
	ds_read_b32 v145, v245
	ds_read_b32 v133, v242
	ds_read_b32 v227, v141 offset:128
	ds_read_b32 v226, v243 offset:128
	ds_read_b32 v141, v241 offset:128
	s_waitcnt lgkmcnt(9)
	v_pk_add_f32 v[106:107], v[106:107], v[234:235]
	v_pk_add_f32 v[104:105], v[104:105], v[230:231]
	s_waitcnt lgkmcnt(4)
	v_pk_add_f32 v[110:111], v[110:111], v[144:145]
	s_waitcnt lgkmcnt(3)
	v_pk_add_f32 v[108:109], v[108:109], v[132:133]
	v_pk_add_f32 v[82:83], v[82:83], v[142:143]
	v_pk_add_f32 v[80:81], v[80:81], v[134:135]
	v_pk_add_f32 v[86:87], v[86:87], v[228:229]
	v_pk_add_f32 v[84:85], v[84:85], v[146:147]
	v_pk_add_f32 v[90:91], v[90:91], v[236:237]
	v_pk_add_f32 v[88:89], v[88:89], v[232:233]
	s_waitcnt lgkmcnt(1)
	v_pk_add_f32 v[94:95], v[94:95], v[226:227]
	s_waitcnt lgkmcnt(0)
	v_pk_add_f32 v[92:93], v[92:93], v[140:141]

; __device__ __forceinline__ float hsum(float v) { auto rr = __builtin_amdgcn_permlane32_swap(__float_as_uint(v), __float_as_uint(v), false, false); return __uint_as_float(rr[0]) + __uint_as_float(rr[1]); }
; __device__ __forceinline__ void da_unit(LAS unsigned char* lds, const AttnP& P, int seqbase, int S, int h, int qb, float lam) {
;     ...
;         int tid3 = threadIdx.x; asm volatile("" : "+v"(tid3));
;         f32x4* stash = (f32x4*)(P.stash + (size_t)blockIdx.x * 32768 + tid3 * 64);
;         if (map == 0) {
;             const float inv = 1.0f / hsum(l);
; #pragma unroll
;             for (int db = 0; db < 4; ++db)
; #pragma unroll
;                 for (int g = 0; g < 4; ++g) stash[db * 4 + g] = (f32x4){o[db][4 * g], o[db][4 * g + 1], o[db][4 * g + 2], o[db][4 * g + 3]} * inv;
;         } else {
;             const float inv = lam / hsum(l);
; #pragma unroll
;             for (int db = 0; db < 4; ++db)
; #pragma unroll
;                 for (int g = 0; g < 4; ++g) {
;                     const f32x4 st = stash[db * 4 + g];
; #pragma unroll
;                     for (int e = 0; e < 4; ++e) { const float a = st[e] - o[db][4 * g + e] * inv; o[db][4 * g + e] = a; ss += a * a; }
;                 }
;         }
.LBB0_450:
	s_setprio 0
	v_mov_b32_e32 v2, v151
	s_and_b64 vcc, exec, s[58:59]
	v_lshrrev_b32_e32 v3, 6, v2
	v_and_b32_e32 v2, 63, v2
	v_lshlrev_b32_e32 v3, 14, v3
	v_lshl_or_b32 v246, v2, 4, v3
	v_add_u32_e32 v247, 0x1000, v246
	v_add_u32_e32 v248, 0x2000, v246
	v_add_u32_e32 v249, 0x3000, v246
	v_lshlrev_b32_e32 v3, 4, v151
	v_add_u32_e32 v2, 0x18000, v3
	v_add_u32_e32 v3, 0x1c700, v3
	s_cbranch_vccz .LBB0_452
	global_load_dwordx4 v[98:101], v247, s[20:21] offset:3072
	global_load_dwordx4 v[102:105], v248, s[20:21] offset:0
	global_load_dwordx4 v[132:135], v248, s[20:21] offset:1024
	global_load_dwordx4 v[136:139], v248, s[20:21] offset:2048
	global_load_dwordx4 v[140:143], v248, s[20:21] offset:3072
	global_load_dwordx4 v[144:147], v249, s[20:21] offset:3072
	global_load_dwordx4 v[160:163], v249, s[20:21] offset:2048
	global_load_dwordx4 v[164:167], v249, s[20:21] offset:1024
	global_load_dwordx4 v[168:171], v249, s[20:21] offset:0
	ds_read_b128 v[4:7], v2 offset:0
	ds_read_b128 v[8:11], v2 offset:8192
	ds_read_b128 v[12:15], v3 offset:0
	ds_read_b128 v[80:83], v3 offset:8192
	ds_read_b128 v[84:87], v3 offset:16384
	ds_read_b128 v[88:91], v3 offset:24576
	ds_read_b128 v[92:95], v3 offset:32768
	v_mov_b32_e32 v96, v0
	v_mov_b32_e32 v97, v0
	s_nop 1
	v_permlane32_swap_b32_e32 v96, v97
	v_add_f32_e32 v96, v96, v97
	v_div_scale_f32 v97, s[10:11], v96, v96, v211
	v_rcp_f32_e32 v106, v97
	v_div_scale_f32 v107, vcc, v211, v96, v211
	v_fma_f32 v108, -v97, v106, 1.0
	v_fmac_f32_e32 v106, v108, v106
	v_mul_f32_e32 v108, v107, v106
	v_fma_f32 v109, -v97, v108, v107
	v_fmac_f32_e32 v108, v109, v106
	v_fma_f32 v97, -v97, v108, v107
	v_div_fmas_f32 v97, v97, v106, v108
	v_div_fixup_f32 v172, v97, v96, v211
	s_waitcnt lgkmcnt(0)
	v_pk_fma_f32 v[130:131], v[64:65], v[172:173], v[4:5] op_sel_hi:[1,0,1] neg_lo:[1,0,0] neg_hi:[1,0,0]
	v_pk_fma_f32 v[128:129], v[66:67], v[172:173], v[6:7] op_sel_hi:[1,0,1] neg_lo:[1,0,0] neg_hi:[1,0,0]
	s_waitcnt vmcnt(14)
	v_pk_fma_f32 v[126:127], v[68:69], v[172:173], v[8:9] op_sel_hi:[1,0,1] neg_lo:[1,0,0] neg_hi:[1,0,0]
	s_waitcnt vmcnt(12)
	v_pk_fma_f32 v[116:117], v[76:77], v[172:173], v[80:81] op_sel_hi:[1,0,1] neg_lo:[1,0,0] neg_hi:[1,0,0]
	v_pk_mul_f32 v[80:81], v[130:131], v[130:131]
	v_pk_fma_f32 v[114:115], v[78:79], v[172:173], v[82:83] op_sel_hi:[1,0,1] neg_lo:[1,0,0] neg_hi:[1,0,0]
	v_add_f32_e32 v80, v222, v80
	v_pk_mul_f32 v[82:83], v[128:129], v[128:129]
	v_add_f32_e32 v80, v81, v80
	v_add_f32_e32 v80, v82, v80
	s_waitcnt vmcnt(11)
	v_pk_fma_f32 v[118:119], v[48:49], v[172:173], v[84:85] op_sel_hi:[1,0,1] neg_lo:[1,0,0] neg_hi:[1,0,0]
	v_pk_mul_f32 v[84:85], v[126:127], v[126:127]
	v_add_f32_e32 v80, v83, v80
	v_pk_fma_f32 v[124:125], v[70:71], v[172:173], v[10:11] op_sel_hi:[1,0,1] neg_lo:[1,0,0] neg_hi:[1,0,0]
	v_add_f32_e32 v80, v84, v80
	s_waitcnt vmcnt(10)
	v_pk_fma_f32 v[110:111], v[52:53], v[172:173], v[88:89] op_sel_hi:[1,0,1] neg_lo:[1,0,0] neg_hi:[1,0,0]
	v_pk_mul_f32 v[88:89], v[124:125], v[124:125]
	v_add_f32_e32 v80, v85, v80
	v_pk_fma_f32 v[122:123], v[72:73], v[172:173], v[12:13] op_sel_hi:[1,0,1] neg_lo:[1,0,0] neg_hi:[1,0,0]
	v_add_f32_e32 v80, v88, v80
	s_waitcnt vmcnt(9)
	v_pk_fma_f32 v[106:107], v[56:57], v[172:173], v[92:93] op_sel_hi:[1,0,1] neg_lo:[1,0,0] neg_hi:[1,0,0]
	s_waitcnt vmcnt(8)
	v_pk_fma_f32 v[92:93], v[60:61], v[172:173], v[98:99] op_sel_hi:[1,0,1] neg_lo:[1,0,0] neg_hi:[1,0,0]
	v_pk_mul_f32 v[98:99], v[122:123], v[122:123]
	v_add_f32_e32 v80, v89, v80
	v_pk_fma_f32 v[120:121], v[74:75], v[172:173], v[14:15] op_sel_hi:[1,0,1] neg_lo:[1,0,0] neg_hi:[1,0,0]
	v_add_f32_e32 v80, v98, v80
	v_pk_fma_f32 v[108:109], v[54:55], v[172:173], v[90:91] op_sel_hi:[1,0,1] neg_lo:[1,0,0] neg_hi:[1,0,0]
	v_pk_fma_f32 v[90:91], v[62:63], v[172:173], v[100:101] op_sel_hi:[1,0,1] neg_lo:[1,0,0] neg_hi:[1,0,0]
	v_pk_mul_f32 v[100:101], v[120:121], v[120:121]
	v_add_f32_e32 v80, v99, v80
	v_add_f32_e32 v80, v100, v80
	v_pk_fma_f32 v[96:97], v[58:59], v[172:173], v[94:95] op_sel_hi:[1,0,1] neg_lo:[1,0,0] neg_hi:[1,0,0]
	s_waitcnt vmcnt(7)
	v_pk_fma_f32 v[94:95], v[32:33], v[172:173], v[102:103] op_sel_hi:[1,0,1] neg_lo:[1,0,0] neg_hi:[1,0,0]
	v_pk_mul_f32 v[102:103], v[116:117], v[116:117]
	v_add_f32_e32 v80, v101, v80
	v_add_f32_e32 v80, v102, v80
	v_pk_fma_f32 v[112:113], v[50:51], v[172:173], v[86:87] op_sel_hi:[1,0,1] neg_lo:[1,0,0] neg_hi:[1,0,0]
	v_pk_fma_f32 v[86:87], v[34:35], v[172:173], v[104:105] op_sel_hi:[1,0,1] neg_lo:[1,0,0] neg_hi:[1,0,0]
	v_pk_mul_f32 v[104:105], v[114:115], v[114:115]
	v_add_f32_e32 v80, v103, v80
	v_add_f32_e32 v80, v104, v80
	s_waitcnt vmcnt(6)
; __device__ __forceinline__ void da_unit(LAS unsigned char* lds, const AttnP& P, int seqbase, int S, int h, int qb, float lam) {
;     ...
;             for (int db = 0; db < 4; ++db)
; #pragma unroll
;                 for (int g = 0; g < 4; ++g) {
;                     const f32x4 st = stash[db * 4 + g];
; #pragma unroll
;                     for (int e = 0; e < 4; ++e) { const float a = st[e] - o[db][4 * g + e] * inv; o[db][4 * g + e] = a; ss += a * a; }
;                 }
	v_pk_fma_f32 v[14:15], v[36:37], v[172:173], v[132:133] op_sel_hi:[1,0,1] neg_lo:[1,0,0] neg_hi:[1,0,0]
	v_pk_mul_f32 v[132:133], v[118:119], v[118:119]
	v_add_f32_e32 v80, v105, v80
	v_add_f32_e32 v80, v132, v80
	v_pk_fma_f32 v[12:13], v[38:39], v[172:173], v[134:135] op_sel_hi:[1,0,1] neg_lo:[1,0,0] neg_hi:[1,0,0]
	v_pk_mul_f32 v[134:135], v[112:113], v[112:113]
	v_add_f32_e32 v80, v133, v80
	v_add_f32_e32 v80, v134, v80
	s_waitcnt vmcnt(5)
	v_pk_fma_f32 v[10:11], v[40:41], v[172:173], v[136:137] op_sel_hi:[1,0,1] neg_lo:[1,0,0] neg_hi:[1,0,0]
	v_pk_mul_f32 v[136:137], v[110:111], v[110:111]
	v_add_f32_e32 v80, v135, v80
	v_add_f32_e32 v80, v136, v80
	v_pk_fma_f32 v[8:9], v[42:43], v[172:173], v[138:139] op_sel_hi:[1,0,1] neg_lo:[1,0,0] neg_hi:[1,0,0]
	v_pk_mul_f32 v[138:139], v[108:109], v[108:109]
	v_add_f32_e32 v80, v137, v80
	v_add_f32_e32 v80, v138, v80
	s_waitcnt vmcnt(4)
	v_pk_fma_f32 v[6:7], v[44:45], v[172:173], v[140:141] op_sel_hi:[1,0,1] neg_lo:[1,0,0] neg_hi:[1,0,0]
	v_pk_mul_f32 v[140:141], v[106:107], v[106:107]
	v_add_f32_e32 v80, v139, v80
	v_add_f32_e32 v80, v140, v80
	v_pk_fma_f32 v[4:5], v[46:47], v[172:173], v[142:143] op_sel_hi:[1,0,1] neg_lo:[1,0,0] neg_hi:[1,0,0]
	v_pk_mul_f32 v[142:143], v[96:97], v[96:97]
	v_add_f32_e32 v80, v141, v80
	v_add_f32_e32 v80, v142, v80
	v_pk_mul_f32 v[174:175], v[92:93], v[92:93]
	v_add_f32_e32 v80, v143, v80
	v_add_f32_e32 v80, v174, v80
	v_pk_mul_f32 v[176:177], v[90:91], v[90:91]
	v_add_f32_e32 v80, v175, v80
	v_add_f32_e32 v80, v176, v80
	v_pk_mul_f32 v[178:179], v[94:95], v[94:95]
	v_add_f32_e32 v80, v177, v80
	v_add_f32_e32 v80, v178, v80
	v_pk_mul_f32 v[180:181], v[86:87], v[86:87]
	v_add_f32_e32 v80, v179, v80
	v_add_f32_e32 v80, v180, v80
	v_pk_mul_f32 v[182:183], v[14:15], v[14:15]
	v_add_f32_e32 v80, v181, v80
	v_add_f32_e32 v80, v182, v80
	v_pk_mul_f32 v[184:185], v[12:13], v[12:13]
	v_add_f32_e32 v80, v183, v80
	v_add_f32_e32 v80, v184, v80
	v_pk_mul_f32 v[186:187], v[10:11], v[10:11]
	v_add_f32_e32 v80, v185, v80
	v_add_f32_e32 v80, v186, v80
	v_pk_mul_f32 v[188:189], v[8:9], v[8:9]
	v_add_f32_e32 v80, v187, v80
	v_add_f32_e32 v80, v188, v80
	v_pk_mul_f32 v[190:191], v[6:7], v[6:7]
	v_add_f32_e32 v80, v189, v80
	v_add_f32_e32 v80, v190, v80
	v_add_f32_e32 v82, v191, v80
	v_pk_mul_f32 v[80:81], v[4:5], v[4:5]
	s_waitcnt vmcnt(0)
	v_pk_fma_f32 v[102:103], v[16:17], v[172:173], v[168:169] op_sel_hi:[1,0,1] neg_lo:[1,0,0] neg_hi:[1,0,0]
	v_add_f32_e32 v80, v80, v82
	v_add_f32_e32 v82, v81, v80
	v_pk_mul_f32 v[80:81], v[102:103], v[102:103]
	v_pk_fma_f32 v[104:105], v[18:19], v[172:173], v[170:171] op_sel_hi:[1,0,1] neg_lo:[1,0,0] neg_hi:[1,0,0]
	v_add_f32_e32 v80, v80, v82
	v_add_f32_e32 v82, v81, v80
	v_pk_mul_f32 v[80:81], v[104:105], v[104:105]
	v_pk_fma_f32 v[98:99], v[20:21], v[172:173], v[164:165] op_sel_hi:[1,0,1] neg_lo:[1,0,0] neg_hi:[1,0,0]
	v_add_f32_e32 v80, v80, v82
	v_add_f32_e32 v82, v81, v80
	v_pk_mul_f32 v[80:81], v[98:99], v[98:99]
	v_pk_fma_f32 v[100:101], v[22:23], v[172:173], v[166:167] op_sel_hi:[1,0,1] neg_lo:[1,0,0] neg_hi:[1,0,0]
	v_add_f32_e32 v80, v80, v82
	v_add_f32_e32 v82, v81, v80
	v_pk_mul_f32 v[80:81], v[100:101], v[100:101]
	v_pk_fma_f32 v[88:89], v[24:25], v[172:173], v[160:161] op_sel_hi:[1,0,1] neg_lo:[1,0,0] neg_hi:[1,0,0]
	v_add_f32_e32 v80, v80, v82
	v_add_f32_e32 v82, v81, v80
	v_pk_mul_f32 v[80:81], v[88:89], v[88:89]
	v_pk_fma_f32 v[84:85], v[26:27], v[172:173], v[162:163] op_sel_hi:[1,0,1] neg_lo:[1,0,0] neg_hi:[1,0,0]
	v_add_f32_e32 v80, v80, v82
	v_add_f32_e32 v82, v81, v80
	v_pk_mul_f32 v[80:81], v[84:85], v[84:85]
	s_nop 0
	v_add_f32_e32 v80, v80, v82
	v_add_f32_e32 v132, v81, v80
	v_pk_fma_f32 v[80:81], v[28:29], v[172:173], v[144:145] op_sel_hi:[1,0,1] neg_lo:[1,0,0] neg_hi:[1,0,0]
	s_nop 0
	v_pk_mul_f32 v[82:83], v[80:81], v[80:81]
	s_nop 0
	v_add_f32_e32 v82, v82, v132
	v_add_f32_e32 v134, v83, v82
	v_pk_fma_f32 v[82:83], v[30:31], v[172:173], v[146:147] op_sel_hi:[1,0,1] neg_lo:[1,0,0] neg_hi:[1,0,0]
	s_nop 0
	v_pk_mul_f32 v[132:133], v[82:83], v[82:83]
	s_nop 0
	v_add_f32_e32 v132, v132, v134
	v_add_f32_e32 v132, v133, v132
	s_cbranch_execz .LBB0_453
	s_branch .LBB0_454
